# MIX seam split: idle workgroup flushes attention rows during the gating units; XCD-local seam + epoch waits
# baseline (speedup 1.0000x reference)
; template <class T> __device__ __forceinline__ T* as_global(T* p) { return (T*)(GAS T*)p; }
; #define SEAM(k) do { if ((k) + 1 < hi) { if ((k) == 0) grid.sync(); else { xcd_barrier(bar); if (DUP & 4) xcd_barrier(bar); } } } while (0)
; #define SEAM(k) do { } while (0)
; #define WSBASE() GAS unsigned char* wsg_ = (GAS unsigned char*)a.ws; asm volatile("" : "+s"(wsg_)); unsigned char* ws = (unsigned char*)wsg_; i64* stats = (i64*)(ws + WS_STATS); i64* st = stats + (size_t)(6 * l) * MTOK; unsigned char* wl = ws + WS_W + (size_t)l * WL_STRIDE; (void)st; (void)wl
; __global__ void __launch_bounds__(NWAVES * 64, 2) fwd_kernel(Args a) {
;     ...
;                 if (!(SKIP & 8)) { WSBASE();
;                   for (int u = cu; u < MTOK / 128; u += G) for (int rp = 0; rp < ((DUP & 2) ? 2 : 1); ++rp)
;                     sgu_unit(lds, u * 128, (const bf16_t*)(ws + WS_GT), (const bf16_t*)(ws + WS_U), (const bf16_t*)(ws + WS_SGUW) + (size_t)l * 4 * 16384, as_global(a.in[10]) + l * 512, as_global(a.in[7]) + l * DH, as_global(a.in[8]) + l * DH,
;                              st + 3 * MTOK, st + 4 * MTOK, (bf16_t*)(ws + WS_MIX), wave, lane); }
;                 SEAM(pb + 3);
.LBB0_1109:
	s_waitcnt vmcnt(0)
	s_barrier
	s_mov_b64 s[28:29], exec
	v_readlane_b32 s4, v254, 7
	v_readlane_b32 s5, v254, 8
	s_nop 1
	s_and_b64 exec, s[28:29], s[4:5]
	s_cbranch_execz .Lma_done
	v_mov_b32_e32 v14, 0x23084
	ds_read_b32 v14, v14
	s_waitcnt lgkmcnt(0)
	v_readfirstlane_b32 s6, v14
	s_nop 3
	s_cmp_eq_u32 s6, 0
	s_cbranch_scc1 .Lma_done
	v_readlane_b32 s4, v253, 44
	v_readlane_b32 s5, v253, 45
	v_mov_b32_e32 v11, 1
	s_nop 3
	global_atomic_add v1, v11, s[4:5] offset:192
	s_lshr_b32 s6, s2, 3
	s_cmp_lg_u32 s6, 31
	s_cbranch_scc1 .Lma_done
	v_mov_b32_e32 v14, 0x23098
	v_mov_b32_e32 v12, 32
	ds_add_rtn_u32 v13, v14, v12
	s_waitcnt lgkmcnt(0)
	v_add_u32_e32 v13, 32, v13
	s_mov_b32 s6, 0
.Lma_poll:
	global_load_dword v12, v1, s[4:5] offset:192 sc1
	s_waitcnt vmcnt(0)
	v_cmp_ge_u32_e32 vcc, v12, v13
	s_cbranch_vccnz .Lma_flush
	s_add_i32 s6, s6, 1
	s_cmp_lt_u32 s6, 0x2000
	s_cbranch_scc0 .Lma_flush
	s_sleep 2
	s_branch .Lma_poll
.Lma_flush:
	buffer_wbl2 sc1
	s_waitcnt vmcnt(0)
	v_readlane_b32 s4, v252, 34
	v_readlane_b32 s5, v252, 35
	s_nop 4
	global_atomic_add v1, v11, s[4:5] offset:-192
.Lma_done:
	s_mov_b64 exec, s[28:29]
	v_readlane_b32 s4, v253, 54
	v_readlane_b32 s5, v253, 55
	s_mov_b64 s[46:47], s[94:95]
	s_andn2_b64 vcc, exec, s[4:5]
	s_cbranch_vccnz .LBB0_1131
	v_readlane_b32 s4, v252, 51
	v_readlane_b32 s5, v252, 52
	s_lshl_b64 s[4:5], s[4:5], 3
	s_add_u32 s4, s46, s4
	s_addc_u32 s5, s47, s5
	s_add_u32 s28, s46, 0x12400000
	s_addc_u32 s29, s47, 0
	v_readlane_b32 s6, v255, 4
	s_add_u32 s6, s46, s6
	s_addc_u32 s7, s47, 0
	s_add_u32 s30, s6, 0x15500000
	s_addc_u32 s31, s7, 0
	s_add_i32 s8, s55, 8
	s_add_i32 s9, s55, 16
	s_add_i32 s10, s55, 24
	s_add_i32 s11, s55, 32
	s_add_i32 s12, s55, 40
	s_add_i32 s13, s55, 48
	s_add_i32 s14, s55, 56
	s_add_i32 s15, s55, 64
	s_add_i32 s16, s55, 0x48
	s_add_i32 s17, s55, 0x50
	s_add_i32 s18, s55, 0x58
	s_add_i32 s19, s55, 0x60
	s_add_i32 s20, s55, 0x68
	s_add_i32 s21, s55, 0x70
	s_add_i32 s42, s55, 0x78
	s_and_b32 s6, s36, 0xffffffc0
	s_lshl_b32 s22, s55, 10
	s_lshl_b32 s7, s8, 6
	s_lshl_b32 s23, s8, 10
	s_lshl_b32 s8, s9, 6
	s_lshl_b32 s26, s9, 10
	s_lshl_b32 s9, s10, 6
	s_lshl_b32 s27, s10, 10
	s_lshl_b32 s10, s11, 6
	s_lshl_b32 s40, s11, 10
	s_lshl_b32 s11, s12, 6
	s_lshl_b32 s41, s12, 10
	s_lshl_b32 s12, s13, 6
	s_lshl_b32 s50, s13, 10
	s_lshl_b32 s13, s14, 6
	s_lshl_b32 s51, s14, 10
	s_lshl_b32 s14, s15, 6
	s_lshl_b32 s71, s15, 10
	s_lshl_b32 s15, s16, 6
	s_lshl_b32 s88, s16, 10
	s_lshl_b32 s16, s17, 6
	s_lshl_b32 s89, s17, 10
	s_lshl_b32 s17, s18, 6
	s_lshl_b32 s90, s18, 10
	s_lshl_b32 s18, s19, 6
	s_lshl_b32 s91, s19, 10
	s_lshl_b32 s19, s20, 6
	s_lshl_b32 s92, s20, 10
	s_lshl_b32 s20, s21, 6
	s_lshl_b32 s93, s21, 10
	s_lshl_b32 s21, s42, 6
	s_lshl_b32 s94, s42, 10
	s_and_b32 s48, s36, 64
	s_and_b32 s42, s36, 0xffffff80
	s_add_u32 s36, s4, 0x80000
	s_addc_u32 s52, s5, 0
	s_add_u32 s53, s4, 0x60000
	s_addc_u32 s54, s5, 0
	s_ashr_i32 s43, s42, 31
	s_lshl_b64 s[4:5], s[42:43], 1
	s_lshl_b32 s43, s48, 1
	s_add_u32 s4, s46, s4
	s_addc_u32 s5, s47, s5
	s_add_u32 s4, s4, s43
	s_addc_u32 s5, s5, 0
	s_add_u32 s46, s4, 0xe400000
	s_addc_u32 s47, s5, 0
	s_lshl_b32 s43, s55, 9
	s_add_i32 s43, s43, 0
	s_add_i32 s43, s43, 0x20400
	s_add_u32 s48, s4, 0x13400000
	s_addc_u32 s49, s5, 0
	s_add_i32 s55, s22, 0
	s_add_i32 s76, s23, 0
	s_add_i32 s77, s26, 0
	s_add_i32 s78, s27, 0
	s_add_i32 s79, s40, 0
	s_add_i32 s80, s41, 0
	s_add_i32 s81, s50, 0
	s_add_i32 s82, s51, 0
	s_add_i32 s83, s71, 0
	s_add_i32 s88, s88, 0
	s_add_i32 s89, s89, 0
	s_add_i32 s90, s90, 0
	s_add_i32 s91, s91, 0
	s_add_i32 s92, s92, 0
	s_add_i32 s93, s93, 0
	s_add_i32 s94, s94, 0
	s_and_b32 s96, s2, 7
	s_lshl_b32 s96, s96, 4
	s_lshr_b32 s95, s2, 3
	s_add_i32 s96, s96, s95
	s_lshl_b32 s95, s96, 7
	s_or_b32 s95, s95, 0x70
	s_branch .LBB0_1112

; __device__ __forceinline__ unsigned xb_ld(unsigned* p)              { return __hip_atomic_load(p, __ATOMIC_RELAXED, __HIP_MEMORY_SCOPE_AGENT); }
; __device__ __forceinline__ unsigned xb_add(unsigned* p, unsigned v) { return __hip_atomic_fetch_add(p, v, __ATOMIC_RELAXED, __HIP_MEMORY_SCOPE_AGENT); }
; #define XB_SPIN(cond, bar) do { unsigned _sp = 0; while (cond) { __builtin_amdgcn_s_sleep(8); \
;     if ((++_sp & 255u) == 0u) { if (xb_ld(&(bar)[XB_TMO])) break; if (_sp > XB_SPIN_CAP) { atomicAdd(&(bar)[XB_TMO], 1u); break; } } } } while (0)
; #define SEAM(k) do { if ((k) + 1 < hi) { if ((k) == 0) grid.sync(); else { xcd_barrier(bar); if (DUP & 4) xcd_barrier(bar); } } } while (0)
; #define SEAM(k) do { } while (0)
; __device__ __forceinline__ void xcd_barrier(const XcdBarrier& b) {
;     asm volatile("s_waitcnt vmcnt(0)" ::: "memory");
;     __syncthreads();
;     if (threadIdx.x == 0) {
;         unsigned* bar = b.bar;
;         __builtin_amdgcn_s_waitcnt(0);
;         unsigned nloc = b.st[0], nx = b.st[1];
;         if (nloc == 0u) { xcd_barrier_complete(bar, b.x, nloc, nx); b.st[0] = nloc; b.st[1] = nx; }
;         const unsigned old = xb_add(&bar[XB_XSUB(b.x)], 1u);
;         const unsigned gen = old / nloc;
;         if (old + 1u == (gen + 1u) * nloc) {
;             __builtin_amdgcn_fence(__ATOMIC_RELEASE, "agent");
;             asm volatile("s_waitcnt vmcnt(0)" ::: "memory");
;             const unsigned og = xb_add(&bar[XB_TOP], 1u);
;             const unsigned tg = og / nx;
;             if (og + 1u == (tg + 1u) * nx) xb_add(&bar[XB_TOPGEN], 1u);
;             else XB_SPIN(xb_ld(&bar[XB_TOPGEN]) == tg, bar);
;             __builtin_amdgcn_fence(__ATOMIC_ACQUIRE, "agent");
;             xb_add(&bar[XB_XGEN(b.x)], 1u);
;             asm volatile("s_waitcnt vmcnt(0)" ::: "memory");
;         } else {
;             XB_SPIN(xb_ld(&bar[XB_XGEN(b.x)]) == gen, bar);
;             __builtin_amdgcn_fence(__ATOMIC_ACQUIRE, "agent");
;             asm volatile("s_waitcnt vmcnt(0)" ::: "memory");
;         }
;     }
;     __syncthreads();
; }
; __global__ void __launch_bounds__(NWAVES * 64, 2) fwd_kernel(Args a) {
;     ...
;                 SEAM(pb + 3);
.LBB0_1148:
	v_mov_b32_e32 v14, 0x23084
	ds_read_b32 v14, v14
	s_waitcnt lgkmcnt(0)
	v_readfirstlane_b32 s5, v14
	s_nop 3
	s_cmp_eq_u32 s5, 0
	s_cbranch_scc1 .Lmx_full
	v_readlane_b32 s4, v253, 44
	v_readlane_b32 s5, v253, 45
	v_readlane_b32 s8, v252, 34
	v_readlane_b32 s9, v252, 35
	v_mov_b32_e32 v14, 0x2308c
	ds_add_rtn_u32 v13, v14, v3
	v_mov_b32_e32 v11, 1
	v_mov_b32_e32 v14, 0x2309c
	v_mov_b32_e32 v12, 8
	ds_add_rtn_u32 v10, v14, v12
	global_atomic_add v1, v11, s[4:5] offset:128
	s_waitcnt lgkmcnt(0)
	v_add_u32_e32 v13, v13, v3
	v_add_u32_e32 v10, 8, v10
	s_mov_b32 s6, 0
.Lmx_poll:
	global_load_dword v12, v1, s[4:5] offset:128 sc1
	global_load_dword v9, v1, s[8:9] offset:-192 sc1
	s_waitcnt vmcnt(0)
	v_cmp_ge_u32_e32 vcc, v12, v13
	v_cmp_ge_u32_e64 s[30:31], v9, v10
	s_nop 1
	s_and_b64 vcc, vcc, s[30:31]
	s_cbranch_vccnz .Lmx_done
	s_add_i32 s6, s6, 1
	s_cmp_lt_u32 s6, 0x2000
	s_cbranch_scc0 .Lmx_done
	s_sleep 2
	s_branch .Lmx_poll
.Lmx_done:
	s_lshr_b32 s6, s2, 3
	s_cmp_lg_u32 s6, 31
	s_cbranch_scc1 .Lmx_tail
	global_atomic_add v1, v11, s[8:9] offset:-224

; __device__ __forceinline__ unsigned xb_ld(unsigned* p)              { return __hip_atomic_load(p, __ATOMIC_RELAXED, __HIP_MEMORY_SCOPE_AGENT); }
; __device__ __forceinline__ unsigned xb_add(unsigned* p, unsigned v) { return __hip_atomic_fetch_add(p, v, __ATOMIC_RELAXED, __HIP_MEMORY_SCOPE_AGENT); }
; #define XB_SPIN(cond, bar) do { unsigned _sp = 0; while (cond) { __builtin_amdgcn_s_sleep(8); \
;     if ((++_sp & 255u) == 0u) { if (xb_ld(&(bar)[XB_TMO])) break; if (_sp > XB_SPIN_CAP) { atomicAdd(&(bar)[XB_TMO], 1u); break; } } } } while (0)
; #define SEAM(k) do { if ((k) + 1 < hi) { if ((k) == 0) grid.sync(); else { xcd_barrier(bar); if (DUP & 4) xcd_barrier(bar); } } } while (0)
; #define SEAM(k) do { } while (0)
; __device__ __forceinline__ void xcd_barrier(const XcdBarrier& b) {
;     asm volatile("s_waitcnt vmcnt(0)" ::: "memory");
;     __syncthreads();
;     if (threadIdx.x == 0) {
;         unsigned* bar = b.bar;
;         __builtin_amdgcn_s_waitcnt(0);
;         unsigned nloc = b.st[0], nx = b.st[1];
;         if (nloc == 0u) { xcd_barrier_complete(bar, b.x, nloc, nx); b.st[0] = nloc; b.st[1] = nx; }
;         const unsigned old = xb_add(&bar[XB_XSUB(b.x)], 1u);
;         const unsigned gen = old / nloc;
;         if (old + 1u == (gen + 1u) * nloc) {
;             __builtin_amdgcn_fence(__ATOMIC_RELEASE, "agent");
;             asm volatile("s_waitcnt vmcnt(0)" ::: "memory");
;             const unsigned og = xb_add(&bar[XB_TOP], 1u);
;             const unsigned tg = og / nx;
;             if (og + 1u == (tg + 1u) * nx) xb_add(&bar[XB_TOPGEN], 1u);
;             else XB_SPIN(xb_ld(&bar[XB_TOPGEN]) == tg, bar);
;             __builtin_amdgcn_fence(__ATOMIC_ACQUIRE, "agent");
;             xb_add(&bar[XB_XGEN(b.x)], 1u);
;             asm volatile("s_waitcnt vmcnt(0)" ::: "memory");
;         } else {
;             XB_SPIN(xb_ld(&bar[XB_XGEN(b.x)]) == gen, bar);
;             __builtin_amdgcn_fence(__ATOMIC_ACQUIRE, "agent");
;             asm volatile("s_waitcnt vmcnt(0)" ::: "memory");
;         }
;     }
;     __syncthreads();
; }
; __global__ void __launch_bounds__(NWAVES * 64, 2) fwd_kernel(Args a) {
;     ...
;                 SEAM(pb + 4);
.LBB0_1241:
	v_mov_b32_e32 v14, 0x23084
	ds_read_b32 v14, v14
	s_waitcnt lgkmcnt(0)
	v_readfirstlane_b32 s5, v14
	s_nop 3
	s_cmp_eq_u32 s5, 0
	s_cbranch_scc1 .Lout_full
	v_readlane_b32 s4, v252, 34
	v_readlane_b32 s5, v252, 35
	s_and_b32 s6, s2, 7
	s_lshl_b32 s6, s6, 3
	s_bfe_u32 s7, s2, 0x30003
	s_or_b32 s6, s6, s7
	s_lshl_b32 s6, s6, 5
	s_addk_i32 s6, 0x3600
	s_add_u32 s4, s4, s6
	s_addc_u32 s5, s5, 0
	v_mov_b32_e32 v14, 0x23088
	v_mov_b32_e32 v12, 4
	ds_add_rtn_u32 v13, v14, v12
	v_mov_b32_e32 v11, 1
	s_nop 1
	global_atomic_add v1, v11, s[4:5]
	buffer_inv sc1
	s_waitcnt lgkmcnt(0)
	v_add_u32_e32 v13, 4, v13
	s_mov_b32 s8, 0
	v_readlane_b32 s6, v252, 34
	v_readlane_b32 s7, v252, 35
	v_mov_b32_e32 v14, 0x230a0
	v_mov_b32_e32 v10, 8
	ds_add_rtn_u32 v10, v14, v10
	s_waitcnt lgkmcnt(0)
	v_add_u32_e32 v10, 8, v10
.Lout_lpoll:
	global_load_dword v12, v1, s[4:5] sc1
	global_load_dword v9, v1, s[6:7] offset:-224 sc1
	s_waitcnt vmcnt(0)
	v_cmp_ge_u32_e32 vcc, v12, v13
	v_cmp_ge_u32_e64 s[30:31], v9, v10
	s_nop 1
	s_and_b64 vcc, vcc, s[30:31]
	s_cbranch_vccnz .Lout_ldone
	s_add_i32 s8, s8, 1
	s_cmp_lt_u32 s8, 0x2000
	s_cbranch_scc0 .Lout_ldone
	s_sleep 2
	s_branch .Lout_lpoll
